# adds FFN(0) weight-conversion items done by idle workgroups in the in-proj(0) tail (static split) on top of saddr-form GEMM loads
# speedup vs baseline: 1.0048x; 1.0013x over previous
.LBB0_43:
	s_or_b64 exec, exec, s[4:5]
	v_readfirstlane_b32 s52, v0
	s_cmp_eq_u32 s51, 0x2100
	s_cselect_b32 s100, 4608, 0
	s_add_i32 s52, s52, s100
	s_cmp_ge_i32 s52, s51
	s_mov_b64 s[4:5], -1
	s_cbranch_scc1 .LBB0_38
	s_mov_b32 s53, 0
	s_branch .LBB0_47

.LBB0_226:
	s_cselect_b32 s32, 1, 0
	v_readlane_b32 s7, v254, 0
	v_readlane_b32 s11, v254, 52
	v_readlane_b32 s18, v254, 5
	s_nop 3
	s_cmp_lt_u32 s7, 208
	s_cbranch_scc1 .Lcvt_0_skip
	s_cmp_lg_u32 s11, 0
	s_cbranch_scc1 .Lcvt_0_skip
	s_lshr_b32 s18, s18, 6
	s_sub_u32 s7, s7, 208
	s_lshl_b32 s7, s7, 3
	s_add_u32 s7, s7, s18
	s_add_u32 s7, s7, 0
	s_mov_b32 s80, 0
.Lcvt_0_loop:
	s_mul_i32 s31, s80, 384
	s_add_u32 s31, s31, s7
	s_cmp_ge_u32 s31, 4608
	s_cbranch_scc1 .Lcvt_0_skip
	s_mov_b32 s5, 0
	s_mov_b32 s46, 0
	s_branch .Lcv_item
.Lcv_ret_0:
	s_add_u32 s80, s80, 1
	s_cmp_lt_u32 s80, 12
	s_cbranch_scc1 .Lcvt_0_loop
.Lcvt_0_skip:
	v_mbcnt_lo_u32_b32 v146, -1, 0
	v_mbcnt_hi_u32_b32 v146, -1, v146
	v_readlane_b32 s7, v254, 5
	s_nop 3
	v_add_u32_e32 v146, s7, v146
	s_cmp_lg_u32 s32, 0
	s_waitcnt vmcnt(0)
	v_cmp_eq_u32_e32 vcc, 0, v146
	s_waitcnt vmcnt(0)
	s_barrier
	s_and_saveexec_b64 s[2:3], vcc
	s_cbranch_execz .LBB0_257
	v_readlane_b32 s4, v254, 1
	v_readlane_b32 s5, v254, 2
	v_readlane_b32 s6, v254, 3
	s_lshl_b32 s16, s6, 6
	v_readlane_b32 s7, v254, 4
	s_add_i32 s46, s16, 0x500
	s_waitcnt vmcnt(0) expcnt(0) lgkmcnt(0)
	v_mov_b32_e32 v0, s7
	s_lshl_b64 s[6:7], s[46:47], 2
	s_add_u32 s6, s4, s6
	s_addc_u32 s7, s5, s7
	v_mov_b64_e32 v[4:5], s[6:7]
	ds_read_b32 v3, v0
	ds_read_b32 v2, v0 offset:4
	flat_atomic_add v4, v[4:5], v234 sc0
	s_waitcnt lgkmcnt(0)
	v_cvt_f32_u32_e32 v0, v3
	v_sub_u32_e32 v5, 0, v3
	v_rcp_iflag_f32_e32 v0, v0
	s_nop 0
	v_mul_f32_e32 v0, 0x4f7ffffe, v0
	v_cvt_u32_f32_e32 v0, v0
	v_mul_lo_u32 v5, v5, v0
	v_mul_hi_u32 v5, v0, v5
	v_add_u32_e32 v0, v0, v5
	s_waitcnt vmcnt(0)
	v_mul_hi_u32 v0, v4, v0
	v_mul_lo_u32 v5, v0, v3
	v_sub_u32_e32 v5, v4, v5
	v_add_u32_e32 v6, 1, v0
	v_cmp_ge_u32_e32 vcc, v5, v3
	v_add_u32_e32 v4, 1, v4
	s_nop 0
	v_cndmask_b32_e32 v0, v0, v6, vcc
	v_sub_u32_e32 v6, v5, v3
	v_cndmask_b32_e32 v5, v5, v6, vcc
	v_add_u32_e32 v6, 1, v0
	v_cmp_ge_u32_e32 vcc, v5, v3
	s_nop 1
	v_cndmask_b32_e32 v0, v0, v6, vcc
	v_mul_lo_u32 v5, v3, v0
	v_add_u32_e32 v3, v5, v3
	v_cmp_ne_u32_e32 vcc, v4, v3
	s_and_saveexec_b64 s[6:7], vcc
	s_xor_b64 s[6:7], exec, s[6:7]
	s_cbranch_execz .LBB0_240
	s_add_i32 s46, s16, 0x900
	s_lshl_b64 s[8:9], s[46:47], 2
	s_add_u32 s10, s4, s8
	s_addc_u32 s11, s5, s9
	v_mov_b64_e32 v[2:3], s[10:11]
	buffer_inv sc1
	flat_load_dword v2, v[2:3] sc1
	s_waitcnt vmcnt(0) lgkmcnt(0)
	v_cmp_eq_u32_e32 vcc, v2, v0
	s_and_saveexec_b64 s[8:9], vcc
	s_cbranch_execz .LBB0_239
	s_mov_b32 s17, 1
	s_mov_b64 s[12:13], 0
	s_branch .LBB0_231

.LBB0_504:
	s_or_b64 exec, exec, s[60:61]
	v_readfirstlane_b32 s95, v2
	s_mov_b32 s100, 0
	s_cmp_eq_u32 s91, 0x2100
	s_cselect_b32 s100, 0, s100
	s_cmp_eq_u32 s91, 0xd00
	s_cselect_b32 s100, 0, s100
	s_add_i32 s95, s95, s100
	s_cmp_ge_i32 s95, s91
	s_mov_b64 s[60:61], -1
	s_cbranch_scc1 .LBB0_499
	s_add_i32 s81, s85, s95
	s_mov_b32 s6, 0
	s_branch .LBB0_508

.Lcv_item:
	s_cmp_eq_u32 s5, 0
	s_cbranch_scc1 .Lcv_q_Q01
	s_cmp_eq_u32 s5, 1
	s_cbranch_scc1 .Lcv_q_Q10
	s_cmp_eq_u32 s5, 2
	s_cbranch_scc1 .Lcv_q_Q11
	s_cmp_eq_u32 s5, 3
	s_cbranch_scc1 .Lcv_q_Q20
	s_cmp_eq_u32 s5, 4
	s_cbranch_scc1 .Lcv_q_Q21
	s_cmp_eq_u32 s5, 5
	s_cbranch_scc1 .Lcv_q_Q30
	s_cmp_eq_u32 s5, 6
	s_cbranch_scc1 .Lcv_q_Q31
	s_branch .Lcv_done
.Lcv_q_Q01:
	s_cmp_lt_u32 s31, 5632
	s_cbranch_scc1 .Lcv_s_Q01_0
	s_branch .Lcv_s_Q01_1
.Lcv_s_Q01_0:
	s_sub_u32 s35, s31, 0
	s_mov_b32 s98, 264
	s_mov_b32 s100, 0x0
	s_mov_b32 s101, 0x7400000
	s_movk_i32 s40, 2048
	s_movk_i32 s43, 11264
	s_movk_i32 s55, 176
	s_mov_b32 s61, 0x1745d18
	s_mov_b32 s64, 1
	s_branch .Lcv_core
.Lcv_s_Q01_1:
	s_sub_u32 s35, s31, 5632
	s_mov_b32 s98, 288
	s_mov_b32 s100, 0x0
	s_mov_b32 s101, 0x12400000
	s_movk_i32 s40, 5632
	s_movk_i32 s43, 2048
	s_movk_i32 s55, 32
	s_mov_b32 s61, 0x8000001
	s_mov_b32 s64, 0
	s_branch .Lcv_core
.Lcv_q_Q10:
	s_cmp_lt_u32 s31, 2496
	s_cbranch_scc1 .Lcv_s_Q10_0
	s_cmp_lt_u32 s31, 3520
	s_cbranch_scc1 .Lcv_s_Q10_1
	s_cmp_lt_u32 s31, 3712
	s_cbranch_scc1 .Lcv_s_Q10_2
	s_branch .Lcv_s_Q10_3
.Lcv_s_Q10_0:
	s_sub_u32 s35, s31, 0
	s_mov_b32 s98, 184
	s_mov_b32 s100, 0x0
	s_mov_b32 s101, 0x1800000
	s_movk_i32 s40, 2048
	s_movk_i32 s43, 4960
	s_movk_i32 s55, 78
	s_mov_b32 s61, 0x3483484
	s_mov_b32 s64, 2
	s_branch .Lcv_core
.Lcv_s_Q10_1:
	s_sub_u32 s35, s31, 2496
	s_mov_b32 s98, 192
	s_mov_b32 s100, 0x0
	s_mov_b32 s101, 0x5c00000
	s_movk_i32 s40, 2048
	s_movk_i32 s43, 2048
	s_movk_i32 s55, 32
	s_mov_b32 s61, 0x8000001
	s_mov_b32 s64, 0
	s_branch .Lcv_core
.Lcv_s_Q10_2:
	s_sub_u32 s35, s31, 3520
	s_mov_b32 s98, 240
	s_mov_b32 s100, 0x0
	s_mov_b32 s101, 0x17c00000
	s_movk_i32 s40, 512
	s_movk_i32 s43, 1536
	s_movk_i32 s55, 24
	s_mov_b32 s61, 0xaaaaaab
	s_mov_b32 s64, 0
	s_branch .Lcv_core
.Lcv_s_Q10_3:
	s_sub_u32 s35, s31, 3712
	s_mov_b32 s98, 256
	s_mov_b32 s100, 0x0
	s_mov_b32 s101, 0x17f00000
	s_movk_i32 s40, 256
	s_movk_i32 s43, 2048
	s_movk_i32 s55, 32
	s_mov_b32 s61, 0x8000001
	s_mov_b32 s64, 0
	s_branch .Lcv_core

.Lcv_s_Q11_0:
	s_sub_u32 s35, s31, 0
	s_mov_b32 s98, 264
	s_mov_b32 s100, 0x5800000
	s_mov_b32 s101, 0xa000000
	s_movk_i32 s40, 2048
	s_movk_i32 s43, 11264
	s_movk_i32 s55, 176
	s_mov_b32 s61, 0x1745d18
	s_mov_b32 s64, 1
	s_branch .Lcv_core
.Lcv_s_Q11_1:
	s_sub_u32 s35, s31, 5632
	s_mov_b32 s98, 288
	s_mov_b32 s100, 0x2c00000
	s_mov_b32 s101, 0x13a00000
	s_movk_i32 s40, 5632
	s_movk_i32 s43, 2048
	s_movk_i32 s55, 32
	s_mov_b32 s61, 0x8000001
	s_mov_b32 s64, 0
	s_branch .Lcv_core
.Lcv_q_Q20:
	s_cmp_lt_u32 s31, 2304
	s_cbranch_scc1 .Lcv_s_Q20_0
	s_branch .Lcv_s_Q20_1
.Lcv_s_Q20_0:
	s_sub_u32 s35, s31, 0
	s_mov_b32 s98, 136
	s_mov_b32 s100, 0x2400000
	s_mov_b32 s101, 0x2c00000
	s_movk_i32 s40, 2048
	s_movk_i32 s43, 4608
	s_movk_i32 s55, 72
	s_mov_b32 s61, 0x38e38e4
	s_mov_b32 s64, 0
	s_branch .Lcv_core
.Lcv_s_Q20_1:
	s_sub_u32 s35, s31, 2304
	s_mov_b32 s98, 144
	s_mov_b32 s100, 0x1000000
	s_mov_b32 s101, 0x6400000
	s_movk_i32 s40, 2048
	s_movk_i32 s43, 2048
	s_movk_i32 s55, 32
	s_mov_b32 s61, 0x8000001
	s_mov_b32 s64, 0
	s_branch .Lcv_core

.Lcv_s_Q21_0:
	s_sub_u32 s35, s31, 0
	s_mov_b32 s98, 264
	s_mov_b32 s100, 0xb000000
	s_mov_b32 s101, 0xcc00000
	s_movk_i32 s40, 2048
	s_movk_i32 s43, 11264
	s_movk_i32 s55, 176
	s_mov_b32 s61, 0x1745d18
	s_mov_b32 s64, 1
	s_branch .Lcv_core
.Lcv_s_Q21_1:
	s_sub_u32 s35, s31, 5632
	s_mov_b32 s98, 288
	s_mov_b32 s100, 0x5800000
	s_mov_b32 s101, 0x15000000
	s_movk_i32 s40, 5632
	s_movk_i32 s43, 2048
	s_movk_i32 s55, 32
	s_mov_b32 s61, 0x8000001
	s_mov_b32 s64, 0
	s_branch .Lcv_core

.Lcv_s_Q30_0:
	s_sub_u32 s35, s31, 0
	s_mov_b32 s98, 184
	s_mov_b32 s100, 0x26c0000
	s_mov_b32 s101, 0x4000000
	s_movk_i32 s40, 2048
	s_movk_i32 s43, 4960
	s_movk_i32 s55, 78
	s_mov_b32 s61, 0x3483484
	s_mov_b32 s64, 2
	s_branch .Lcv_core
.Lcv_s_Q30_1:
	s_sub_u32 s35, s31, 2496
	s_mov_b32 s98, 192
	s_mov_b32 s100, 0x1000000
	s_mov_b32 s101, 0x6c00000
	s_movk_i32 s40, 2048
	s_movk_i32 s43, 2048
	s_movk_i32 s55, 32
	s_mov_b32 s61, 0x8000001
	s_mov_b32 s64, 0
	s_branch .Lcv_core
.Lcv_s_Q30_2:
	s_sub_u32 s35, s31, 3520
	s_mov_b32 s98, 240
	s_mov_b32 s100, 0x300000
	s_mov_b32 s101, 0x17d80000
	s_movk_i32 s40, 512
	s_movk_i32 s43, 1536
	s_movk_i32 s55, 24
	s_mov_b32 s61, 0xaaaaaab
	s_mov_b32 s64, 0
	s_branch .Lcv_core
.Lcv_s_Q30_3:
	s_sub_u32 s35, s31, 3712
	s_mov_b32 s98, 256
	s_mov_b32 s100, 0x200000
	s_mov_b32 s101, 0x18000000
	s_movk_i32 s40, 256
	s_movk_i32 s43, 2048
	s_movk_i32 s55, 32
	s_mov_b32 s61, 0x8000001
	s_mov_b32 s64, 0
	s_branch .Lcv_core

.Lcv_s_Q31_0:
	s_sub_u32 s35, s31, 0
	s_mov_b32 s98, 264
	s_mov_b32 s100, 0x10800000
	s_mov_b32 s101, 0xf800000
	s_movk_i32 s40, 2048
	s_movk_i32 s43, 11264
	s_movk_i32 s55, 176
	s_mov_b32 s61, 0x1745d18
	s_mov_b32 s64, 1
	s_branch .Lcv_core
.Lcv_s_Q31_1:
	s_sub_u32 s35, s31, 5632
	s_mov_b32 s98, 288
	s_mov_b32 s100, 0x8400000
	s_mov_b32 s101, 0x16600000
	s_movk_i32 s40, 5632
	s_movk_i32 s43, 2048
	s_movk_i32 s55, 32
	s_mov_b32 s61, 0x8000001
	s_mov_b32 s64, 0
	s_branch .Lcv_core
.Lcv_core:
	v_readlane_b32 s66, v254, 10
	v_readlane_b32 s67, v254, 11
	v_readlane_b32 s62, v254, 8
	v_readlane_b32 s63, v254, 9
	s_nop 3
	s_add_u32 s66, s66, s98
	s_addc_u32 s67, s67, 0
	s_load_dwordx2 s[8:9], s[66:67], 0x0
	s_add_u32 s38, s62, s101
	s_addc_u32 s39, s63, 0
	v_mbcnt_lo_u32_b32 v204, -1, 0
	v_mbcnt_hi_u32_b32 v204, -1, v204
	s_mul_hi_u32 s5, s35, s61
	s_mul_i32 s11, s5, s55
	s_sub_u32 s11, s35, s11
	s_lshl_b32 s5, s5, 6
	s_lshl_b32 s11, s11, 6
	s_lshl_b32 s45, s5, 1
	s_mul_i32 s31, s5, s43
	s_lshl_b32 s31, s31, 2
	s_lshl_b32 s44, s43, 2
	v_add_u32_e32 v205, s11, v204
	v_cmp_gt_u32_e32 vcc, s43, v205
	v_lshlrev_b32_e32 v205, 2, v205
	s_nop 1
	v_cndmask_b32_e32 v205, 0, v205, vcc
	s_waitcnt lgkmcnt(0)
	s_add_u32 s8, s8, s100
	s_addc_u32 s9, s9, 0
	s_add_u32 s8, s8, s31
	s_addc_u32 s9, s9, 0
	global_load_dword v130, v205, s[8:9]
	s_add_u32 s8, s8, s44
	s_addc_u32 s9, s9, 0
	global_load_dword v131, v205, s[8:9]
	s_add_u32 s8, s8, s44
	s_addc_u32 s9, s9, 0
	global_load_dword v132, v205, s[8:9]
	s_add_u32 s8, s8, s44
	s_addc_u32 s9, s9, 0
	global_load_dword v133, v205, s[8:9]
	s_add_u32 s8, s8, s44
	s_addc_u32 s9, s9, 0
	global_load_dword v134, v205, s[8:9]
	s_add_u32 s8, s8, s44
	s_addc_u32 s9, s9, 0
	global_load_dword v135, v205, s[8:9]
	s_add_u32 s8, s8, s44
	s_addc_u32 s9, s9, 0
	global_load_dword v136, v205, s[8:9]
	s_add_u32 s8, s8, s44
	s_addc_u32 s9, s9, 0
	global_load_dword v137, v205, s[8:9]
	s_add_u32 s8, s8, s44
	s_addc_u32 s9, s9, 0
	global_load_dword v138, v205, s[8:9]
	s_add_u32 s8, s8, s44
	s_addc_u32 s9, s9, 0
	global_load_dword v139, v205, s[8:9]
	s_add_u32 s8, s8, s44
	s_addc_u32 s9, s9, 0
	global_load_dword v140, v205, s[8:9]
	s_add_u32 s8, s8, s44
	s_addc_u32 s9, s9, 0
	global_load_dword v141, v205, s[8:9]
	s_add_u32 s8, s8, s44
	s_addc_u32 s9, s9, 0
	global_load_dword v142, v205, s[8:9]
	s_add_u32 s8, s8, s44
	s_addc_u32 s9, s9, 0
	global_load_dword v143, v205, s[8:9]
	s_add_u32 s8, s8, s44
	s_addc_u32 s9, s9, 0
	global_load_dword v144, v205, s[8:9]
	s_add_u32 s8, s8, s44
	s_addc_u32 s9, s9, 0
	global_load_dword v145, v205, s[8:9]
	s_add_u32 s8, s8, s44
	s_addc_u32 s9, s9, 0
	global_load_dword v146, v205, s[8:9]
	s_add_u32 s8, s8, s44
	s_addc_u32 s9, s9, 0
	global_load_dword v147, v205, s[8:9]
	s_add_u32 s8, s8, s44
	s_addc_u32 s9, s9, 0
	global_load_dword v148, v205, s[8:9]
	s_add_u32 s8, s8, s44
	s_addc_u32 s9, s9, 0
	global_load_dword v149, v205, s[8:9]
	s_add_u32 s8, s8, s44
	s_addc_u32 s9, s9, 0
	global_load_dword v150, v205, s[8:9]
	s_add_u32 s8, s8, s44
	s_addc_u32 s9, s9, 0
	global_load_dword v151, v205, s[8:9]
	s_add_u32 s8, s8, s44
	s_addc_u32 s9, s9, 0
	global_load_dword v152, v205, s[8:9]
	s_add_u32 s8, s8, s44
	s_addc_u32 s9, s9, 0
	global_load_dword v153, v205, s[8:9]
	s_add_u32 s8, s8, s44
	s_addc_u32 s9, s9, 0
	global_load_dword v154, v205, s[8:9]
	s_add_u32 s8, s8, s44
	s_addc_u32 s9, s9, 0
	global_load_dword v155, v205, s[8:9]
	s_add_u32 s8, s8, s44
	s_addc_u32 s9, s9, 0
	global_load_dword v156, v205, s[8:9]
	s_add_u32 s8, s8, s44
	s_addc_u32 s9, s9, 0
	global_load_dword v157, v205, s[8:9]
	s_add_u32 s8, s8, s44
	s_addc_u32 s9, s9, 0
	global_load_dword v158, v205, s[8:9]
	s_add_u32 s8, s8, s44
	s_addc_u32 s9, s9, 0
	global_load_dword v159, v205, s[8:9]
	s_add_u32 s8, s8, s44
	s_addc_u32 s9, s9, 0
	global_load_dword v160, v205, s[8:9]
	s_add_u32 s8, s8, s44
	s_addc_u32 s9, s9, 0
	global_load_dword v161, v205, s[8:9]
	s_add_u32 s8, s8, s44
	s_addc_u32 s9, s9, 0
	global_load_dword v162, v205, s[8:9]
	s_add_u32 s8, s8, s44
	s_addc_u32 s9, s9, 0
	global_load_dword v163, v205, s[8:9]
	s_add_u32 s8, s8, s44
	s_addc_u32 s9, s9, 0
	global_load_dword v164, v205, s[8:9]
	s_add_u32 s8, s8, s44
	s_addc_u32 s9, s9, 0
	global_load_dword v165, v205, s[8:9]
	s_add_u32 s8, s8, s44
	s_addc_u32 s9, s9, 0
	global_load_dword v166, v205, s[8:9]
	s_add_u32 s8, s8, s44
	s_addc_u32 s9, s9, 0
	global_load_dword v167, v205, s[8:9]
	s_add_u32 s8, s8, s44
	s_addc_u32 s9, s9, 0
	global_load_dword v168, v205, s[8:9]
	s_add_u32 s8, s8, s44
	s_addc_u32 s9, s9, 0
	global_load_dword v169, v205, s[8:9]
	s_add_u32 s8, s8, s44
	s_addc_u32 s9, s9, 0
	global_load_dword v170, v205, s[8:9]
	s_add_u32 s8, s8, s44
	s_addc_u32 s9, s9, 0
	global_load_dword v171, v205, s[8:9]
	s_add_u32 s8, s8, s44
	s_addc_u32 s9, s9, 0
	global_load_dword v172, v205, s[8:9]
	s_add_u32 s8, s8, s44
	s_addc_u32 s9, s9, 0
	global_load_dword v173, v205, s[8:9]
	s_add_u32 s8, s8, s44
	s_addc_u32 s9, s9, 0
	global_load_dword v174, v205, s[8:9]
	s_add_u32 s8, s8, s44
	s_addc_u32 s9, s9, 0
	global_load_dword v175, v205, s[8:9]
	s_add_u32 s8, s8, s44
	s_addc_u32 s9, s9, 0
	global_load_dword v176, v205, s[8:9]
	s_add_u32 s8, s8, s44
	s_addc_u32 s9, s9, 0
	global_load_dword v177, v205, s[8:9]
	s_add_u32 s8, s8, s44
	s_addc_u32 s9, s9, 0
	global_load_dword v178, v205, s[8:9]
	s_add_u32 s8, s8, s44
	s_addc_u32 s9, s9, 0
	global_load_dword v179, v205, s[8:9]
	s_add_u32 s8, s8, s44
	s_addc_u32 s9, s9, 0
	global_load_dword v180, v205, s[8:9]
	s_add_u32 s8, s8, s44
	s_addc_u32 s9, s9, 0
	global_load_dword v181, v205, s[8:9]
	s_add_u32 s8, s8, s44
	s_addc_u32 s9, s9, 0
	global_load_dword v182, v205, s[8:9]
	s_add_u32 s8, s8, s44
	s_addc_u32 s9, s9, 0
	global_load_dword v183, v205, s[8:9]
	s_add_u32 s8, s8, s44
	s_addc_u32 s9, s9, 0
	global_load_dword v184, v205, s[8:9]
	s_add_u32 s8, s8, s44
	s_addc_u32 s9, s9, 0
	global_load_dword v185, v205, s[8:9]
	s_add_u32 s8, s8, s44
	s_addc_u32 s9, s9, 0
	global_load_dword v186, v205, s[8:9]
	s_add_u32 s8, s8, s44
	s_addc_u32 s9, s9, 0
	global_load_dword v187, v205, s[8:9]
	s_add_u32 s8, s8, s44
	s_addc_u32 s9, s9, 0
	global_load_dword v188, v205, s[8:9]
	s_add_u32 s8, s8, s44
	s_addc_u32 s9, s9, 0
	global_load_dword v189, v205, s[8:9]
	s_add_u32 s8, s8, s44
	s_addc_u32 s9, s9, 0
	global_load_dword v190, v205, s[8:9]
	s_add_u32 s8, s8, s44
	s_addc_u32 s9, s9, 0
	global_load_dword v191, v205, s[8:9]
	s_add_u32 s8, s8, s44
	s_addc_u32 s9, s9, 0
	global_load_dword v192, v205, s[8:9]
	s_add_u32 s8, s8, s44
	s_addc_u32 s9, s9, 0
	global_load_dword v193, v205, s[8:9]
	s_mul_i32 s5, s18, 0x2400
	v_mul_u32_u24_e32 v206, 0x90, v204
	v_add_u32_e32 v206, s5, v206
	v_lshrrev_b32_e32 v208, 3, v204
	v_and_b32_e32 v209, 7, v204
	v_mul_u32_u24_e32 v207, 0x90, v208
	v_lshl_add_u32 v207, v209, 4, v207
	v_add_u32_e32 v207, s5, v207
	v_lshlrev_b32_e32 v212, 4, v209
	v_add_u32_e32 v212, s45, v212
	v_add_u32_e32 v208, s11, v208
	s_lshl_b32 s31, s40, 1
	v_mad_u32_u24 v211, v208, s31, v212
	s_mov_b32 s98, 0
	s_mov_b32 s99, 0
	s_cmp_eq_u32 s64, 0
	s_cbranch_scc1 .Lcv_pd
	s_cmp_eq_u32 s64, 1
	s_cbranch_scc0 .Lcv_p2
	s_cmp_ge_u32 s11, 5632
	s_cselect_b32 s100, 5632, 0
	s_cselect_b32 s101, 128, 0
	s_sub_u32 s100, s11, s100
	s_lshr_b32 s5, s100, 7
	s_lshl_b32 s5, s5, 8
	s_and_b32 s100, s100, 127
	s_add_u32 s5, s5, s100
	s_add_u32 s5, s5, s101
	s_sub_u32 s98, s5, s11
	s_mov_b32 s99, s98
	s_branch .Lcv_pd
.Lcv_p2:
	s_cmp_lt_u32 s11, 4096
	s_cbranch_scc1 .Lcv_pd
	s_mov_b32 s98, -32
	s_mov_b32 s99, -32
	s_cmp_eq_u32 s11, 4096
	s_cselect_b32 s98, 832, s98
.Lcv_pd:
	s_waitcnt vmcnt(0)
	v_cvt_pk_bf16_f32 v130, v130, v131
	v_cvt_pk_bf16_f32 v131, v132, v133
	v_cvt_pk_bf16_f32 v132, v134, v135
	v_cvt_pk_bf16_f32 v133, v136, v137
	v_cvt_pk_bf16_f32 v134, v138, v139
	v_cvt_pk_bf16_f32 v135, v140, v141
	v_cvt_pk_bf16_f32 v136, v142, v143
	v_cvt_pk_bf16_f32 v137, v144, v145
	v_cvt_pk_bf16_f32 v138, v146, v147
	v_cvt_pk_bf16_f32 v139, v148, v149
	v_cvt_pk_bf16_f32 v140, v150, v151
	v_cvt_pk_bf16_f32 v141, v152, v153
	v_cvt_pk_bf16_f32 v142, v154, v155
	v_cvt_pk_bf16_f32 v143, v156, v157
	v_cvt_pk_bf16_f32 v144, v158, v159
	v_cvt_pk_bf16_f32 v145, v160, v161
	v_cvt_pk_bf16_f32 v146, v162, v163
	v_cvt_pk_bf16_f32 v147, v164, v165
	v_cvt_pk_bf16_f32 v148, v166, v167
	v_cvt_pk_bf16_f32 v149, v168, v169
	v_cvt_pk_bf16_f32 v150, v170, v171
	v_cvt_pk_bf16_f32 v151, v172, v173
	v_cvt_pk_bf16_f32 v152, v174, v175
	v_cvt_pk_bf16_f32 v153, v176, v177
	v_cvt_pk_bf16_f32 v154, v178, v179
	v_cvt_pk_bf16_f32 v155, v180, v181
	v_cvt_pk_bf16_f32 v156, v182, v183
	v_cvt_pk_bf16_f32 v157, v184, v185
	v_cvt_pk_bf16_f32 v158, v186, v187
	v_cvt_pk_bf16_f32 v159, v188, v189
	v_cvt_pk_bf16_f32 v160, v190, v191
	v_cvt_pk_bf16_f32 v161, v192, v193
	ds_write_b128 v206, v[130:133]
	ds_write_b128 v206, v[134:137] offset:16
	ds_write_b128 v206, v[138:141] offset:32
	ds_write_b128 v206, v[142:145] offset:48
	ds_write_b128 v206, v[146:149] offset:64
	ds_write_b128 v206, v[150:153] offset:80
	ds_write_b128 v206, v[154:157] offset:96
	ds_write_b128 v206, v[158:161] offset:112
	s_waitcnt lgkmcnt(0)
	ds_read_b128 v[162:165], v207
	ds_read_b128 v[166:169], v207 offset:1152
	ds_read_b128 v[170:173], v207 offset:2304
	ds_read_b128 v[174:177], v207 offset:3456
	ds_read_b128 v[178:181], v207 offset:4608
	ds_read_b128 v[182:185], v207 offset:5760
	ds_read_b128 v[186:189], v207 offset:6912
	ds_read_b128 v[190:193], v207 offset:8064
	s_waitcnt lgkmcnt(0)
	s_mov_b64 s[78:79], exec
	s_add_i32 s5, s98, 0
	s_mul_i32 s5, s5, s31
	s_sub_u32 s100, s43, 0
	v_add_u32_e32 v210, s5, v211
	v_cmp_gt_u32_e32 vcc, s100, v208
	s_and_b64 exec, s[78:79], vcc
	global_store_dwordx4 v210, v[162:165], s[38:39]
	s_mov_b64 exec, s[78:79]
	s_add_i32 s5, s98, 8
	s_mul_i32 s5, s5, s31
	s_sub_u32 s100, s43, 8
	v_add_u32_e32 v210, s5, v211
	v_cmp_gt_u32_e32 vcc, s100, v208
	s_and_b64 exec, s[78:79], vcc
	global_store_dwordx4 v210, v[166:169], s[38:39]
	s_mov_b64 exec, s[78:79]
	s_add_i32 s5, s98, 16
	s_mul_i32 s5, s5, s31
	s_sub_u32 s100, s43, 16
	v_add_u32_e32 v210, s5, v211
	v_cmp_gt_u32_e32 vcc, s100, v208
	s_and_b64 exec, s[78:79], vcc
	global_store_dwordx4 v210, v[170:173], s[38:39]
	s_mov_b64 exec, s[78:79]
	s_add_i32 s5, s98, 24
	s_mul_i32 s5, s5, s31
	s_sub_u32 s100, s43, 24
	v_add_u32_e32 v210, s5, v211
	v_cmp_gt_u32_e32 vcc, s100, v208
	s_and_b64 exec, s[78:79], vcc
	global_store_dwordx4 v210, v[174:177], s[38:39]
	s_mov_b64 exec, s[78:79]
	s_add_i32 s5, s99, 32
	s_mul_i32 s5, s5, s31
	s_sub_u32 s100, s43, 32
	v_add_u32_e32 v210, s5, v211
	v_cmp_gt_u32_e32 vcc, s100, v208
	s_and_b64 exec, s[78:79], vcc
	global_store_dwordx4 v210, v[178:181], s[38:39]
	s_mov_b64 exec, s[78:79]
	s_add_i32 s5, s99, 40
	s_mul_i32 s5, s5, s31
	s_sub_u32 s100, s43, 40
	v_add_u32_e32 v210, s5, v211
	v_cmp_gt_u32_e32 vcc, s100, v208
	s_and_b64 exec, s[78:79], vcc
	global_store_dwordx4 v210, v[182:185], s[38:39]
	s_mov_b64 exec, s[78:79]
	s_add_i32 s5, s99, 48
	s_mul_i32 s5, s5, s31
	s_sub_u32 s100, s43, 48
	v_add_u32_e32 v210, s5, v211
	v_cmp_gt_u32_e32 vcc, s100, v208
	s_and_b64 exec, s[78:79], vcc
	global_store_dwordx4 v210, v[186:189], s[38:39]
	s_mov_b64 exec, s[78:79]
	s_add_i32 s5, s99, 56
	s_mul_i32 s5, s5, s31
	s_sub_u32 s100, s43, 56
	v_add_u32_e32 v210, s5, v211
	v_cmp_gt_u32_e32 vcc, s100, v208
	s_and_b64 exec, s[78:79], vcc
	global_store_dwordx4 v210, v[190:193], s[38:39]
	s_mov_b64 exec, s[78:79]
.Lcv_done:
	s_cmp_eq_u32 s46, 0
	s_cbranch_scc1 .Lcv_ret_0
	s_branch .Lcv_ret_0

.LBB0_828:
	s_or_b64 exec, exec, s[62:63]
	v_readfirstlane_b32 s41, v2
	s_mov_b32 s100, 0
	s_cmp_eq_u32 s16, 0x2100
	s_cselect_b32 s100, 0, s100
	s_add_i32 s41, s41, s100
	s_cmp_ge_i32 s41, s16
	s_mov_b64 s[62:63], -1
	s_cbranch_scc1 .LBB0_823
	s_add_i32 s44, s40, s41
	s_mov_b32 s45, 0
	s_branch .LBB0_832
